# attention loop rotated (softmax | PV+next QK segments) with two wave halves staggered by one barrier; K tiles fetched two ahead
# speedup vs baseline: 1.0154x; 1.0149x over previous
; #define AT_LOAD(t) do { kr0 = *(const u32x4*)(Kp + (size_t)((t) * 64 + kkey0) * 96 + kc0 * 8); if (k1ok) kr1 = *(const u32x4*)(Kp + (size_t)((t) * 64 + kkey1) * 96 + kc1 * 8); \
;         vr = *(const u32x4*)(Vtp + (size_t)vd * KVLEN + (t) * 64 + vc * 8); } while (0)
; #define AT_STORE(bf) do { *(u32x4*)(Kl + (bf) * AT_KB + kkey0 * AT_KP + kc0 * 16) = kr0; if (k1ok) *(u32x4*)(Kl + (bf) * AT_KB + kkey1 * AT_KP + kc1 * 16) = kr1; \
;         *(u32x2*)(Vl + (bf) * AT_VB + vd * AT_VP + vc * 16) = (u32x2){vr.x, vr.y}; *(u32x2*)(Vl + (bf) * AT_VB + vd * AT_VP + vc * 16 + 8) = (u32x2){vr.z, vr.w}; } while (0)
; DI void attn_unit(int tb_, char* shm, const bf16_t* Qp, const bf16_t* Kp, const bf16_t* Vtp, int nkeys, int nrows, bf16_t* Op) {
;     ...
;     const int kkey0 = tid / 12, kc0 = tid % 12, kkey1 = (tid + 512) / 12, kc1 = (tid + 512) % 12; const bool k1ok = tid < 256;
;     const int vd = tid >> 3, vc = tid & 7;
;     u32x4 kr0, kr1, vr; kr1 = (u32x4){0u, 0u, 0u, 0u};
;     ...
;     const int nt = nkeys >> 6;
;     f32x16 oa0, oa1, ob0, ob1;
; #pragma unroll
;     for (int r = 0; r < 16; ++r) { oa0[r] = 0.f; oa1[r] = 0.f; ob0[r] = 0.f; ob1[r] = 0.f; }
;     float mra = -INFINITY, lsa = 0.f, mrb = -INFINITY, lsb = 0.f;
;     AT_LOAD(0); AT_STORE(0); __syncthreads();
.LBB0_1042:
	s_or_b64 exec, exec, s[20:21]
	s_mul_i32 s20, s34, 0x88000
	s_mul_hi_i32 s21, s34, 0x88000
	s_add_u32 s6, s28, s20
	s_addc_u32 s7, s29, s21
	v_and_b32_e32 v6, 7, v14
	v_ashrrev_i32_e32 v18, 3, v14
	v_mov_b64_e32 v[4:5], s[6:7]
	s_movk_i32 s0, 0x2200
	v_mad_i64_i32 v[4:5], s[6:7], v18, s0, v[4:5]
	v_lshlrev_b32_e32 v12, 4, v6
	v_mov_b32_e32 v13, v189
	v_lshl_add_u64 v[4:5], v[4:5], 0, v[12:13]
	global_load_dwordx4 v[4:7], v[4:5], off
	s_movk_i32 s0, 0xd0
	v_mul_lo_u32 v205, v16, s0
	v_lshlrev_b32_e32 v206, 4, v17
	v_add3_u32 v13, 0, v205, v206
	v_lshlrev_b32_e32 v207, 4, v19
	s_waitcnt vmcnt(0)
	ds_write_b128 v13, v[0:3]
	s_and_saveexec_b64 s[6:7], vcc
	s_xor_b64 s[6:7], exec, s[6:7]
	v_lshlrev_b32_e32 v207, 4, v19
	s_or_saveexec_b64 s[6:7], s[6:7]
	v_mul_lo_u32 v208, v15, s0
	s_xor_b64 exec, exec, s[6:7]
	v_add3_u32 v0, 0, v208, v207
	ds_write_b128 v0, v[176:179]
	s_or_b64 exec, exec, s[6:7]
	s_movk_i32 s36, 0xc0
	s_movk_i32 s0, 0x2200
	v_mad_i64_i32 v[0:1], s[6:7], v16, s36, 0
	v_mad_i64_i32 v[2:3], s[6:7], v18, s0, 0
	s_lshl_b32 s6, s33, 1
	s_and_b32 s6, s6, 0xffffff80
	s_add_i32 s33, s6, 0
	s_movk_i32 s6, 0x88
	v_mul_lo_u32 v16, v18, s6
	v_add3_u32 v209, 0, v16, v12
	v_and_b32_e32 v13, 63, v14
	v_add_u32_e32 v16, 0x6800, v209
	ds_write2_b64 v16, v[4:5], v[6:7] offset1:1
	s_movk_i32 s0, 0xd0
	v_lshlrev_b32_e32 v5, 2, v13
	v_lshlrev_b32_e32 v14, 3, v200
	v_mad_u32_u24 v4, v201, s0, 0
	v_xor_b32_e32 v202, 0x80, v5
	v_mul_i32_i24_e32 v5, 0xffffffb8, v201
	v_add_u32_e32 v210, v4, v188
	v_add3_u32 v204, v4, v5, v14
	v_mov_b64_e32 v[4:5], s[10:11]
	v_cmp_gt_u32_e64 s[6:7], 32, v13
	v_mad_i64_i32 v[4:5], s[36:37], v15, s36, v[4:5]
	v_lshl_add_u64 v[2:3], s[20:21], 0, v[2:3]
	v_mov_b32_e32 v13, v189
	v_lshl_add_u64 v[0:1], s[10:11], 0, v[0:1]
	v_lshl_add_u64 v[4:5], v[10:11], 1, v[4:5]
	v_lshl_add_u64 v[2:3], v[2:3], 0, v[12:13]
	v_lshl_add_u64 v[0:1], v[8:9], 1, v[0:1]
	v_mov_b32_e32 v32, v189
	v_mov_b32_e32 v33, v189
	v_mov_b32_e32 v46, v189
	v_mov_b32_e32 v47, v189
	v_lshl_add_u64 v[192:193], s[12:13], 0, v[4:5]
	v_lshl_add_u64 v[194:195], s[14:15], 0, v[2:3]
	v_lshl_add_u64 v[196:197], s[12:13], 0, v[0:1]
	v_mov_b32_e32 v34, v189
	v_mov_b32_e32 v35, v189
	v_mov_b32_e32 v36, v189
	v_mov_b32_e32 v37, v189
	v_mov_b32_e32 v38, v189
	v_mov_b32_e32 v39, v189
	v_mov_b32_e32 v40, v189
	v_mov_b32_e32 v41, v189
	v_mov_b32_e32 v42, v189
	v_mov_b32_e32 v43, v189
	v_mov_b32_e32 v44, v189
	v_mov_b32_e32 v45, v189
	v_mov_b64_e32 v[62:63], v[46:47]
	v_mov_b64_e32 v[16:17], v[32:33]
	v_mov_b64_e32 v[0:1], v[32:33]
	v_lshl_add_u32 v198, v201, 2, s33
	s_add_i32 s35, s35, 1
	s_mov_b32 s36, 0
	v_mov_b32_e32 v203, 0
	v_mov_b32_e32 v214, 0xff800000
	v_mov_b64_e32 v[60:61], v[44:45]
	v_mov_b64_e32 v[58:59], v[42:43]
	v_mov_b64_e32 v[56:57], v[40:41]
	v_mov_b64_e32 v[54:55], v[38:39]
	v_mov_b64_e32 v[52:53], v[36:37]
	v_mov_b64_e32 v[50:51], v[34:35]
	v_mov_b64_e32 v[48:49], v[32:33]
	v_mov_b64_e32 v[18:19], v[34:35]
	v_mov_b64_e32 v[20:21], v[36:37]
	v_mov_b64_e32 v[22:23], v[38:39]
	v_mov_b64_e32 v[24:25], v[40:41]
	v_mov_b64_e32 v[26:27], v[42:43]
	v_mov_b64_e32 v[28:29], v[44:45]
	v_mov_b64_e32 v[30:31], v[46:47]
	v_mov_b64_e32 v[2:3], v[34:35]
	v_mov_b64_e32 v[4:5], v[36:37]
	v_mov_b64_e32 v[6:7], v[38:39]
	v_mov_b64_e32 v[8:9], v[40:41]
	v_mov_b64_e32 v[10:11], v[42:43]
	v_mov_b64_e32 v[12:13], v[44:45]
	v_mov_b64_e32 v[14:15], v[46:47]
	v_mov_b32_e32 v213, 0xff800000
	v_mov_b32_e32 v199, 0
	s_waitcnt lgkmcnt(0)
	s_barrier
	global_load_dwordx4 v[184:187], v[196:197], off
	s_and_saveexec_b64 s[10:11], s[8:9]
	s_cbranch_execz .Lat_pro_k1a
	global_load_dwordx4 v[176:179], v[192:193], off
; #define AT_LOAD(t) do { kr0 = *(const u32x4*)(Kp + (size_t)((t) * 64 + kkey0) * 96 + kc0 * 8); if (k1ok) kr1 = *(const u32x4*)(Kp + (size_t)((t) * 64 + kkey1) * 96 + kc1 * 8); \
;         vr = *(const u32x4*)(Vtp + (size_t)vd * KVLEN + (t) * 64 + vc * 8); } while (0)
; DI void attn_unit(int tb_, char* shm, const bf16_t* Qp, const bf16_t* Kp, const bf16_t* Vtp, int nkeys, int nrows, bf16_t* Op) {
;     ...
;     for (int t = 0; t < nt; ++t) {
;         const int bf = t & 1;
;         if (t + 1 < nt) AT_LOAD(t + 1);
;         if (act) {
;             f32x16 pa0, pa1, pb0, pb1;
; #pragma unroll
;             for (int r = 0; r < 16; ++r) { pa0[r] = 0.f; pa1[r] = 0.f; pb0[r] = 0.f; pb1[r] = 0.f; }
;             const char* kb = Kl + bf * AT_KB + r32 * AT_KP + 16 * hi;
; #pragma unroll
;             for (int s = 0; s < 6; ++s) { const bf16x8 k0 = *(const bf16x8*)(kb + 32 * s); const bf16x8 k1 = *(const bf16x8*)(kb + 32 * AT_KP + 32 * s);
;                 pa0 = __builtin_amdgcn_mfma_f32_32x32x16_bf16(k0, qf0[s], pa0, 0, 0, 0); pa1 = __builtin_amdgcn_mfma_f32_32x32x16_bf16(k1, qf0[s], pa1, 0, 0, 0);
;                 pb0 = __builtin_amdgcn_mfma_f32_32x32x16_bf16(k0, qf1[s], pb0, 0, 0, 0); pb1 = __builtin_amdgcn_mfma_f32_32x32x16_bf16(k1, qf1[s], pb1, 0, 0, 0); }
.Lat_pro_k1a:
	s_or_b64 exec, exec, s[10:11]
	v_lshl_add_u64 v[192:193], v[192:193], 0, s[86:87]
	v_lshl_add_u64 v[196:197], v[196:197], 0, s[86:87]
	s_andn2_b64 vcc, exec, s[18:19]
	s_cbranch_vccnz .Lat_pro_s1_skip
	s_mov_b32 s20, 0
	v_add_u32_e32 v92, s20, v210
	ds_read_b128 v[64:67], v92
	ds_read_b128 v[80:83], v92 offset:32
	ds_read_b128 v[84:87], v92 offset:6656
	ds_read_b128 v[216:219], v92 offset:6688
	s_waitcnt lgkmcnt(3)
	v_mfma_f32_32x32x16_bf16 v[96:111], v[64:67], v[172:175], 0
	v_mfma_f32_32x32x16_bf16 v[64:79], v[64:67], v[148:151], 0
	s_waitcnt lgkmcnt(2)
	v_mfma_f32_32x32x16_bf16 v[96:111], v[80:83], v[168:171], v[96:111]
	v_mfma_f32_32x32x16_bf16 v[64:79], v[80:83], v[140:143], v[64:79]
	ds_read_b128 v[80:83], v92 offset:64
	ds_read_b128 v[88:91], v92 offset:96
	ds_read_b128 v[220:223], v92 offset:6720
	ds_read_b128 v[224:227], v92 offset:6752
	s_waitcnt lgkmcnt(3)
	v_mfma_f32_32x32x16_bf16 v[96:111], v[80:83], v[164:167], v[96:111]
	v_mfma_f32_32x32x16_bf16 v[64:79], v[80:83], v[144:147], v[64:79]
	s_waitcnt lgkmcnt(2)
	v_mfma_f32_32x32x16_bf16 v[96:111], v[88:91], v[160:163], v[96:111]
	v_mfma_f32_32x32x16_bf16 v[64:79], v[88:91], v[136:139], v[64:79]
	ds_read_b128 v[80:83], v92 offset:128
	ds_read_b128 v[88:91], v92 offset:160
	ds_read_b128 v[242:245], v92 offset:6784
	ds_read_b128 v[246:249], v92 offset:6816
	v_mfma_f32_32x32x16_bf16 v[112:127], v[84:87], v[172:175], 0
	s_waitcnt lgkmcnt(3)
	v_mfma_f32_32x32x16_bf16 v[96:111], v[80:83], v[156:159], v[96:111]
	v_mfma_f32_32x32x16_bf16 v[64:79], v[80:83], v[132:135], v[64:79]
	v_mfma_f32_32x32x16_bf16 v[112:127], v[216:219], v[168:171], v[112:127]
	s_waitcnt lgkmcnt(2)
	v_mfma_f32_32x32x16_bf16 v[96:111], v[88:91], v[152:155], v[96:111]
	v_mfma_f32_32x32x16_bf16 v[64:79], v[88:91], v[128:131], v[64:79]
	v_mfma_f32_32x32x16_bf16 v[80:95], v[84:87], v[148:151], 0
	v_mfma_f32_32x32x16_bf16 v[112:127], v[220:223], v[164:167], v[112:127]
	v_mfma_f32_32x32x16_bf16 v[80:95], v[216:219], v[140:143], v[80:95]
	v_mfma_f32_32x32x16_bf16 v[112:127], v[224:227], v[160:163], v[112:127]
	v_mfma_f32_32x32x16_bf16 v[80:95], v[220:223], v[144:147], v[80:95]
	s_waitcnt lgkmcnt(1)
	v_mfma_f32_32x32x16_bf16 v[112:127], v[242:245], v[156:159], v[112:127]
	v_mfma_f32_32x32x16_bf16 v[80:95], v[224:227], v[136:139], v[80:95]
	s_waitcnt lgkmcnt(0)
	v_mfma_f32_32x32x16_bf16 v[112:127], v[246:249], v[152:155], v[112:127]
	v_mfma_f32_32x32x16_bf16 v[80:95], v[242:245], v[132:135], v[80:95]
	v_mfma_f32_32x32x16_bf16 v[80:95], v[246:249], v[128:131], v[80:95]
.Lat_pro_s1_skip:
	s_waitcnt vmcnt(0)
	s_movk_i32 s38, 0x3400
	v_add3_u32 v216, s38, v205, v206
	ds_write_b128 v216, v[184:187]
	s_and_saveexec_b64 s[20:21], s[8:9]
	v_add3_u32 v216, s38, v208, v207
	ds_write_b128 v216, v[176:179]
	s_or_b64 exec, exec, s[20:21]
	s_mov_b32 s36, 0
	global_load_dwordx4 v[184:187], v[196:197], off
	s_and_saveexec_b64 s[10:11], s[8:9]
	s_cbranch_execz .Lat_pro_k1b
	global_load_dwordx4 v[176:179], v[192:193], off
.Lat_pro_k1b:
	s_or_b64 exec, exec, s[10:11]
	global_load_dwordx4 v[180:183], v[194:195], off
	v_lshl_add_u64 v[192:193], v[192:193], 0, s[86:87]
	v_lshl_add_u64 v[194:195], v[194:195], 0, s[72:73]
	v_lshl_add_u64 v[196:197], v[196:197], 0, s[86:87]
	s_cmpk_lt_u32 s1, 0x100
	s_cbranch_scc1 .Lat_loop
	s_waitcnt lgkmcnt(0)
	s_barrier
.Lat_loop:
	s_andn2_b64 vcc, exec, s[18:19]
	s_cbranch_vccnz .Lat_val_skip
	v_max3_f32 v211, v96, v97, v112
	v_max3_f32 v211, v211, v113, v98
	v_max3_f32 v211, v211, v98, v99
	v_max3_f32 v211, v211, v114, v115
	v_max3_f32 v211, v211, v100, v101
	v_max3_f32 v211, v211, v116, v117
	v_max3_f32 v211, v211, v102, v103
	v_max3_f32 v211, v211, v118, v119
	v_max3_f32 v211, v211, v104, v105
	v_max3_f32 v211, v211, v120, v121
	v_max3_f32 v211, v211, v106, v107
	v_max3_f32 v211, v211, v122, v123
	v_max3_f32 v211, v211, v108, v109
	v_max3_f32 v211, v211, v124, v125
	v_max3_f32 v211, v211, v110, v111
	v_max3_f32 v211, v211, v126, v127
	ds_bpermute_b32 v212, v202, v211
	v_max_f32_e32 v211, v211, v211
	s_waitcnt lgkmcnt(0)
	v_max_f32_e32 v212, v212, v212
	v_max_f32_e32 v211, v211, v212
	v_add_f32_e32 v212, 0x41000000, v214
	v_cmp_gt_f32_e32 vcc, v211, v212
	s_cbranch_vccz .Lat_no_rs_a
	v_max_f32_e32 v211, v211, v211
	v_max_f32_e32 v212, v214, v214
	v_max_f32_e32 v211, v212, v211
	v_sub_f32_e32 v212, v214, v211
	v_exp_f32_e32 v212, v212
	s_and_saveexec_b64 s[20:21], s[6:7]
	ds_write_b32 v198, v212 offset:44032
	s_or_b64 exec, exec, s[20:21]
	v_mul_f32_e32 v203, v203, v212
	s_waitcnt lgkmcnt(0)
	v_add_u32_e32 v212, s33, v188
	ds_read_b128 v[214:217], v212 offset:44032
	ds_read_b128 v[218:221], v212 offset:44064
	ds_read_b128 v[222:225], v212 offset:44096
	ds_read_b128 v[226:229], v212 offset:44128
	s_waitcnt lgkmcnt(3)
	v_pk_mul_f32 v[34:35], v[34:35], v[216:217]
	s_waitcnt lgkmcnt(2)
	v_pk_mul_f32 v[36:37], v[36:37], v[218:219]
	s_waitcnt lgkmcnt(1)
	v_pk_mul_f32 v[40:41], v[40:41], v[222:223]
	s_waitcnt lgkmcnt(0)
	v_pk_mul_f32 v[44:45], v[44:45], v[226:227]
	v_pk_mul_f32 v[46:47], v[46:47], v[228:229]
	v_pk_mul_f32 v[42:43], v[42:43], v[224:225]
	v_pk_mul_f32 v[38:39], v[38:39], v[220:221]
	v_pk_mul_f32 v[32:33], v[32:33], v[214:215]
	v_pk_mul_f32 v[60:61], v[60:61], v[226:227]
	v_pk_mul_f32 v[56:57], v[56:57], v[222:223]
	v_pk_mul_f32 v[52:53], v[52:53], v[218:219]
	v_pk_mul_f32 v[62:63], v[62:63], v[228:229]
	v_pk_mul_f32 v[58:59], v[58:59], v[224:225]
	v_pk_mul_f32 v[54:55], v[54:55], v[220:221]
	v_pk_mul_f32 v[50:51], v[50:51], v[216:217]
	v_pk_mul_f32 v[48:49], v[48:49], v[214:215]
	s_branch .Lat_max_b

.Lat_max_b:
	v_max3_f32 v212, v64, v65, v80
	v_max3_f32 v212, v212, v81, v66
	v_max3_f32 v212, v212, v66, v67
	v_max3_f32 v212, v212, v82, v83
	v_max3_f32 v212, v212, v68, v69
	v_max3_f32 v212, v212, v84, v85
	v_max3_f32 v212, v212, v70, v71
	v_max3_f32 v212, v212, v86, v87
	v_max3_f32 v212, v212, v72, v73
	v_max3_f32 v212, v212, v88, v89
	v_max3_f32 v212, v212, v74, v75
	v_max3_f32 v212, v212, v90, v91
	v_max3_f32 v212, v212, v76, v77
	v_max3_f32 v212, v212, v92, v93
	v_max3_f32 v212, v212, v78, v79
	v_max3_f32 v212, v212, v94, v95
	ds_bpermute_b32 v214, v202, v212
	v_max_f32_e32 v212, v212, v212
	s_waitcnt lgkmcnt(0)
	v_max_f32_e32 v214, v214, v214
	v_max_f32_e32 v212, v212, v214
	v_add_f32_e32 v214, 0x41000000, v213
	v_cmp_gt_f32_e32 vcc, v212, v214
	s_cbranch_vccz .Lat_no_rs_b
	v_max_f32_e32 v212, v212, v212
	v_max_f32_e32 v214, v213, v213
	v_max_f32_e32 v212, v214, v212
	v_sub_f32_e32 v213, v213, v212
	v_exp_f32_e32 v213, v213
	s_and_saveexec_b64 s[20:21], s[6:7]
	ds_write_b32 v198, v213 offset:44032
	s_or_b64 exec, exec, s[20:21]
	v_mul_f32_e32 v199, v199, v213
	s_waitcnt lgkmcnt(0)
	v_add_u32_e32 v213, s33, v188
	ds_read_b128 v[214:217], v213 offset:44032
	ds_read_b128 v[218:221], v213 offset:44064
	ds_read_b128 v[222:225], v213 offset:44096
	ds_read_b128 v[226:229], v213 offset:44128
	s_waitcnt lgkmcnt(3)
	v_pk_mul_f32 v[18:19], v[18:19], v[216:217]
	s_waitcnt lgkmcnt(2)
	v_pk_mul_f32 v[20:21], v[20:21], v[218:219]
	s_waitcnt lgkmcnt(1)
	v_pk_mul_f32 v[24:25], v[24:25], v[222:223]
	s_waitcnt lgkmcnt(0)
	v_pk_mul_f32 v[28:29], v[28:29], v[226:227]
	v_pk_mul_f32 v[30:31], v[30:31], v[228:229]
	v_pk_mul_f32 v[26:27], v[26:27], v[224:225]
	v_pk_mul_f32 v[22:23], v[22:23], v[220:221]
	v_pk_mul_f32 v[16:17], v[16:17], v[214:215]
	v_pk_mul_f32 v[12:13], v[12:13], v[226:227]
	v_pk_mul_f32 v[8:9], v[8:9], v[222:223]
	v_pk_mul_f32 v[4:5], v[4:5], v[218:219]
	v_pk_mul_f32 v[14:15], v[14:15], v[228:229]
	v_pk_mul_f32 v[10:11], v[10:11], v[224:225]
	v_pk_mul_f32 v[6:7], v[6:7], v[220:221]
	v_pk_mul_f32 v[2:3], v[2:3], v[216:217]
	v_pk_mul_f32 v[0:1], v[0:1], v[214:215]
	s_branch .Lat_exps

.Lat_exps:
	v_sub_f32_e32 v96, v96, v211
	v_exp_f32_e32 v96, v96
	v_sub_f32_e32 v112, v112, v211
	v_exp_f32_e32 v112, v112
	v_sub_f32_e32 v97, v97, v211
	v_exp_f32_e32 v97, v97
	v_sub_f32_e32 v113, v113, v211
	v_exp_f32_e32 v113, v113
	v_sub_f32_e32 v98, v98, v211
	v_add_f32_e32 v213, 0, v96
	v_exp_f32_e32 v98, v98
	v_sub_f32_e32 v114, v114, v211
	v_add_f32_e32 v213, v112, v213
	v_exp_f32_e32 v114, v114
	v_sub_f32_e32 v99, v99, v211
	v_add_f32_e32 v213, v97, v213
	v_exp_f32_e32 v99, v99
	v_sub_f32_e32 v115, v115, v211
	v_add_f32_e32 v213, v113, v213
	v_exp_f32_e32 v115, v115
	v_sub_f32_e32 v100, v100, v211
	v_add_f32_e32 v213, v98, v213
	v_exp_f32_e32 v214, v100
	v_add_f32_e32 v213, v114, v213
	v_sub_f32_e32 v100, v116, v211
	v_add_f32_e32 v213, v99, v213
	v_exp_f32_e32 v116, v100
	v_sub_f32_e32 v100, v101, v211
	v_sub_f32_e32 v64, v64, v212
	v_add_f32_e32 v213, v115, v213
	v_exp_f32_e32 v215, v100
	v_sub_f32_e32 v100, v117, v211
	v_sub_f32_e32 v101, v102, v211
	v_exp_f32_e32 v64, v64
	v_sub_f32_e32 v80, v80, v212
	v_exp_f32_e32 v117, v100
	v_add_f32_e32 v100, v214, v213
	v_exp_f32_e32 v213, v101
	v_sub_f32_e32 v101, v118, v211
	v_exp_f32_e32 v80, v80
	v_sub_f32_e32 v65, v65, v212
	v_exp_f32_e32 v118, v101
	v_sub_f32_e32 v101, v103, v211
	v_exp_f32_e32 v65, v65
	v_sub_f32_e32 v81, v81, v212
	v_exp_f32_e32 v103, v101
	v_sub_f32_e32 v101, v119, v211
	v_exp_f32_e32 v81, v81
	v_sub_f32_e32 v66, v66, v212
	v_exp_f32_e32 v119, v101
	v_sub_f32_e32 v101, v104, v211
	v_cvt_pk_bf16_f32 v104, v112, v113
	v_add_f32_e32 v112, 0, v64
	v_exp_f32_e32 v66, v66
	v_sub_f32_e32 v82, v82, v212
	v_add_f32_e32 v112, v80, v112
	v_exp_f32_e32 v82, v82
	v_sub_f32_e32 v67, v67, v212
	v_add_f32_e32 v112, v65, v112
	v_exp_f32_e32 v67, v67
	v_sub_f32_e32 v83, v83, v212
	v_add_f32_e32 v112, v81, v112
	v_exp_f32_e32 v83, v83
	v_sub_f32_e32 v68, v68, v212
	v_add_f32_e32 v112, v66, v112
	v_exp_f32_e32 v68, v68
	v_sub_f32_e32 v84, v84, v212
	v_add_f32_e32 v112, v82, v112
	v_exp_f32_e32 v84, v84
	v_sub_f32_e32 v69, v69, v212
	v_add_f32_e32 v112, v67, v112
	v_exp_f32_e32 v69, v69
	v_sub_f32_e32 v85, v85, v212
	v_add_f32_e32 v100, v116, v100
	v_add_f32_e32 v112, v83, v112
	v_exp_f32_e32 v85, v85
	v_sub_f32_e32 v70, v70, v212
	v_add_f32_e32 v100, v215, v100
	v_add_f32_e32 v112, v68, v112
	v_exp_f32_e32 v70, v70
	v_sub_f32_e32 v86, v86, v212
	v_add_f32_e32 v100, v117, v100
	v_add_f32_e32 v112, v84, v112
	v_exp_f32_e32 v86, v86
	v_sub_f32_e32 v71, v71, v212
	v_add_f32_e32 v100, v213, v100
	v_exp_f32_e32 v216, v101
	v_sub_f32_e32 v101, v120, v211
	v_add_f32_e32 v112, v69, v112
	v_exp_f32_e32 v71, v71
	v_sub_f32_e32 v87, v87, v212
	v_add_f32_e32 v100, v118, v100
	v_exp_f32_e32 v120, v101
	v_sub_f32_e32 v101, v105, v211
	v_add_f32_e32 v112, v85, v112
	v_exp_f32_e32 v87, v87
	v_sub_f32_e32 v72, v72, v212
	v_add_f32_e32 v100, v103, v100
	v_exp_f32_e32 v217, v101
	v_sub_f32_e32 v101, v121, v211
	v_add_f32_e32 v112, v70, v112
	v_exp_f32_e32 v72, v72
	v_sub_f32_e32 v88, v88, v212
	v_add_f32_e32 v100, v119, v100
	v_exp_f32_e32 v121, v101
	v_sub_f32_e32 v101, v106, v211
	v_add_f32_e32 v112, v86, v112
	v_exp_f32_e32 v88, v88
	v_sub_f32_e32 v73, v73, v212
	v_add_f32_e32 v100, v216, v100
	v_exp_f32_e32 v218, v101
	v_sub_f32_e32 v101, v122, v211
	v_add_f32_e32 v112, v71, v112
	v_exp_f32_e32 v73, v73
	v_sub_f32_e32 v89, v89, v212
	v_add_f32_e32 v100, v120, v100
	v_exp_f32_e32 v122, v101
	v_sub_f32_e32 v101, v107, v211
	v_add_f32_e32 v112, v87, v112
	v_exp_f32_e32 v89, v89
	v_sub_f32_e32 v74, v74, v212
	v_add_f32_e32 v100, v217, v100
	v_exp_f32_e32 v219, v101
	v_sub_f32_e32 v101, v123, v211
	v_add_f32_e32 v112, v72, v112
	v_exp_f32_e32 v74, v74
	v_sub_f32_e32 v90, v90, v212
	v_add_f32_e32 v100, v121, v100
	v_exp_f32_e32 v123, v101
	v_sub_f32_e32 v101, v108, v211
	v_add_f32_e32 v112, v88, v112
	v_exp_f32_e32 v90, v90
	v_sub_f32_e32 v75, v75, v212
	v_add_f32_e32 v100, v218, v100
	v_exp_f32_e32 v220, v101
	v_sub_f32_e32 v101, v124, v211
	v_add_f32_e32 v112, v73, v112
	v_exp_f32_e32 v75, v75
	v_sub_f32_e32 v91, v91, v212
	v_add_f32_e32 v100, v122, v100
	v_exp_f32_e32 v124, v101
	v_sub_f32_e32 v101, v109, v211
	v_add_f32_e32 v112, v89, v112
	v_exp_f32_e32 v91, v91
	v_sub_f32_e32 v76, v76, v212
	v_add_f32_e32 v100, v219, v100
	v_exp_f32_e32 v221, v101
	v_sub_f32_e32 v101, v125, v211
	v_add_f32_e32 v112, v74, v112
	v_exp_f32_e32 v76, v76
	v_sub_f32_e32 v92, v92, v212
	v_add_f32_e32 v100, v123, v100
	v_exp_f32_e32 v125, v101
	v_sub_f32_e32 v101, v110, v211
	v_add_f32_e32 v112, v90, v112
	v_exp_f32_e32 v92, v92
	v_sub_f32_e32 v77, v77, v212
	v_add_f32_e32 v100, v220, v100
	v_exp_f32_e32 v222, v101
	v_sub_f32_e32 v101, v126, v211
	v_add_f32_e32 v112, v75, v112
	v_exp_f32_e32 v77, v77
	v_sub_f32_e32 v93, v93, v212
	v_add_f32_e32 v100, v124, v100
	v_exp_f32_e32 v126, v101
	v_sub_f32_e32 v101, v111, v211
	v_add_f32_e32 v112, v91, v112
	v_exp_f32_e32 v93, v93
	v_sub_f32_e32 v78, v78, v212
	v_add_f32_e32 v100, v221, v100
	v_exp_f32_e32 v111, v101
	v_sub_f32_e32 v101, v127, v211
	v_add_f32_e32 v112, v76, v112
	v_exp_f32_e32 v78, v78
	v_sub_f32_e32 v94, v94, v212
	v_add_f32_e32 v100, v125, v100
	v_exp_f32_e32 v127, v101
	v_add_f32_e32 v112, v92, v112
	v_exp_f32_e32 v94, v94
	v_sub_f32_e32 v79, v79, v212
	v_add_f32_e32 v100, v222, v100
	v_add_f32_e32 v112, v77, v112
	v_exp_f32_e32 v79, v79
	v_sub_f32_e32 v95, v95, v212
	v_add_f32_e32 v100, v126, v100
	v_add_f32_e32 v112, v93, v112
	v_exp_f32_e32 v95, v95
	v_add_f32_e32 v100, v111, v100
	v_add_f32_e32 v112, v78, v112
	v_add_f32_e32 v223, v127, v100
	v_add_f32_e32 v112, v94, v112
	v_add_f32_e32 v203, v203, v223
	v_add_f32_e32 v112, v79, v112
	v_cvt_pk_bf16_f32 v100, v96, v97
	v_cvt_pk_bf16_f32 v101, v98, v99
	v_cvt_pk_bf16_f32 v102, v214, v215
	v_cvt_pk_bf16_f32 v103, v213, v103
	v_cvt_pk_bf16_f32 v105, v114, v115
	v_cvt_pk_bf16_f32 v106, v116, v117
	v_cvt_pk_bf16_f32 v107, v118, v119
	v_cvt_pk_bf16_f32 v108, v216, v217
	v_cvt_pk_bf16_f32 v109, v218, v219
	v_cvt_pk_bf16_f32 v110, v220, v221
	v_cvt_pk_bf16_f32 v111, v222, v111
	v_cvt_pk_bf16_f32 v96, v120, v121
	v_cvt_pk_bf16_f32 v97, v122, v123
	v_cvt_pk_bf16_f32 v98, v124, v125
	v_cvt_pk_bf16_f32 v99, v126, v127
	v_add_f32_e32 v112, v95, v112
	v_cvt_pk_bf16_f32 v64, v64, v65
	v_cvt_pk_bf16_f32 v65, v66, v67
	v_cvt_pk_bf16_f32 v66, v68, v69
	v_cvt_pk_bf16_f32 v67, v70, v71
	v_cvt_pk_bf16_f32 v68, v80, v81
	v_cvt_pk_bf16_f32 v69, v82, v83
	v_cvt_pk_bf16_f32 v70, v84, v85
	v_cvt_pk_bf16_f32 v71, v86, v87
	v_cvt_pk_bf16_f32 v72, v72, v73
	v_cvt_pk_bf16_f32 v73, v74, v75
	v_cvt_pk_bf16_f32 v74, v76, v77
	v_cvt_pk_bf16_f32 v75, v78, v79
	v_cvt_pk_bf16_f32 v76, v88, v89
	v_cvt_pk_bf16_f32 v77, v90, v91
	v_cvt_pk_bf16_f32 v78, v92, v93
	v_cvt_pk_bf16_f32 v79, v94, v95
	v_add_f32_e32 v199, v199, v112
	v_mov_b32_e32 v214, v211
	v_mov_b32_e32 v213, v212
; #define AT_STORE(bf) do { *(u32x4*)(Kl + (bf) * AT_KB + kkey0 * AT_KP + kc0 * 16) = kr0; if (k1ok) *(u32x4*)(Kl + (bf) * AT_KB + kkey1 * AT_KP + kc1 * 16) = kr1; \
;         *(u32x2*)(Vl + (bf) * AT_VB + vd * AT_VP + vc * 16) = (u32x2){vr.x, vr.y}; *(u32x2*)(Vl + (bf) * AT_VB + vd * AT_VP + vc * 16 + 8) = (u32x2){vr.z, vr.w}; } while (0)
; DI void attn_unit(int tb_, char* shm, const bf16_t* Qp, const bf16_t* Kp, const bf16_t* Vtp, int nkeys, int nrows, bf16_t* Op) {
;     ...
;             __builtin_amdgcn_sched_barrier(0);
;             const char* vb = Vl + bf * AT_VB + r32 * AT_VP + 8 * hi;
; #pragma unroll
;             for (int kh = 0; kh < 2; ++kh) {
;                 u32x2 va0[2], va1[2], vc0[2], vc1[2];
; #pragma unroll
;                 for (int k2 = 0; k2 < 2; ++k2) { const int ks = 2 * kh + k2; va0[k2] = *(const u32x2*)(vb + 32 * ks); va1[k2] = *(const u32x2*)(vb + 32 * ks + 16); vc0[k2] = *(const u32x2*)(vb + 32 * AT_VP + 32 * ks); vc1[k2] = *(const u32x2*)(vb + 32 * AT_VP + 32 * ks + 16); }
; #pragma unroll
;                 for (int k2 = 0; k2 < 2; ++k2) { const int ks = 2 * kh + k2;
;                     const bf16x8 vfa = __builtin_bit_cast(bf16x8, ((u32x4){va0[k2].x, va0[k2].y, va1[k2].x, va1[k2].y})), vfc = __builtin_bit_cast(bf16x8, ((u32x4){vc0[k2].x, vc0[k2].y, vc1[k2].x, vc1[k2].y}));
;                     oa0 = __builtin_amdgcn_mfma_f32_32x32x16_bf16(qa[ks], vfa, oa0, 0, 0, 0); oa1 = __builtin_amdgcn_mfma_f32_32x32x16_bf16(qa[ks], vfc, oa1, 0, 0, 0);
;                     ob0 = __builtin_amdgcn_mfma_f32_32x32x16_bf16(qb4[ks], vfa, ob0, 0, 0, 0); ob1 = __builtin_amdgcn_mfma_f32_32x32x16_bf16(qb4[ks], vfc, ob1, 0, 0, 0); }
;                 __builtin_amdgcn_sched_barrier(0);
;             }
;         }
;         if (t + 1 < nt) AT_STORE(bf ^ 1);
;         __syncthreads();
.Lat_val_skip:
	s_waitcnt lgkmcnt(0)
	s_barrier
	s_and_b32 s37, s36, 1
	s_andn2_b64 vcc, exec, s[18:19]
	s_cbranch_vccnz .Lat_mm_skip
	s_mul_i32 s20, s37, 0x2200
	v_add_u32_e32 v84, s20, v204
	v_add_u32_e32 v88, 0x6800, v84
	v_add_u32_e32 v89, 0x7800, v84
	ds_read2_b64 v[80:83], v88 offset1:2
	ds_read2_b64 v[84:87], v89 offset0:32 offset1:34
	s_waitcnt lgkmcnt(1)
	v_mfma_f32_32x32x16_bf16 v[32:47], v[100:103], v[80:83], v[32:47]
	s_waitcnt lgkmcnt(0)
	v_mfma_f32_32x32x16_bf16 v[48:63], v[100:103], v[84:87], v[48:63]
	v_mfma_f32_32x32x16_bf16 v[16:31], v[64:67], v[80:83], v[16:31]
	ds_read2_b64 v[80:83], v89 offset0:36 offset1:38
	v_mfma_f32_32x32x16_bf16 v[0:15], v[64:67], v[84:87], v[0:15]
	ds_read2_b64 v[64:67], v88 offset0:4 offset1:6
	s_waitcnt lgkmcnt(0)
	v_mfma_f32_32x32x16_bf16 v[32:47], v[108:111], v[64:67], v[32:47]
	v_mfma_f32_32x32x16_bf16 v[48:63], v[108:111], v[80:83], v[48:63]
	v_mfma_f32_32x32x16_bf16 v[16:31], v[72:75], v[64:67], v[16:31]
	v_mfma_f32_32x32x16_bf16 v[0:15], v[72:75], v[80:83], v[0:15]
	ds_read2_b64 v[64:67], v88 offset0:8 offset1:10
	ds_read2_b64 v[72:75], v89 offset0:40 offset1:42
	s_waitcnt lgkmcnt(1)
	v_mfma_f32_32x32x16_bf16 v[32:47], v[104:107], v[64:67], v[32:47]
	s_waitcnt lgkmcnt(0)
	v_mfma_f32_32x32x16_bf16 v[48:63], v[104:107], v[72:75], v[48:63]
	v_mfma_f32_32x32x16_bf16 v[16:31], v[68:71], v[64:67], v[16:31]
	ds_read2_b64 v[64:67], v88 offset0:12 offset1:14
	v_mfma_f32_32x32x16_bf16 v[0:15], v[68:71], v[72:75], v[0:15]
	ds_read2_b64 v[68:71], v89 offset0:44 offset1:46
	s_waitcnt lgkmcnt(1)
	v_mfma_f32_32x32x16_bf16 v[32:47], v[96:99], v[64:67], v[32:47]
	s_waitcnt lgkmcnt(0)
	v_mfma_f32_32x32x16_bf16 v[48:63], v[96:99], v[68:71], v[48:63]
	v_mfma_f32_32x32x16_bf16 v[16:31], v[76:79], v[64:67], v[16:31]
	v_mfma_f32_32x32x16_bf16 v[0:15], v[76:79], v[68:71], v[0:15]
	s_cmp_lt_u32 s36, s35
	s_cbranch_scc0 .Lat_mm_skip
	s_xor_b32 s20, s37, 1
	s_mulk_i32 s20, 0x3400
	v_add_u32_e32 v92, s20, v210
	ds_read_b128 v[64:67], v92
	ds_read_b128 v[80:83], v92 offset:32
	ds_read_b128 v[84:87], v92 offset:6656
	ds_read_b128 v[216:219], v92 offset:6688
	s_waitcnt lgkmcnt(3)
	v_mfma_f32_32x32x16_bf16 v[96:111], v[64:67], v[172:175], 0
	v_mfma_f32_32x32x16_bf16 v[64:79], v[64:67], v[148:151], 0
	s_waitcnt lgkmcnt(2)
	v_mfma_f32_32x32x16_bf16 v[96:111], v[80:83], v[168:171], v[96:111]
	v_mfma_f32_32x32x16_bf16 v[64:79], v[80:83], v[140:143], v[64:79]
	ds_read_b128 v[80:83], v92 offset:64
	ds_read_b128 v[88:91], v92 offset:96
	ds_read_b128 v[220:223], v92 offset:6720
	ds_read_b128 v[224:227], v92 offset:6752
	s_waitcnt lgkmcnt(3)
	v_mfma_f32_32x32x16_bf16 v[96:111], v[80:83], v[164:167], v[96:111]
	v_mfma_f32_32x32x16_bf16 v[64:79], v[80:83], v[144:147], v[64:79]
	s_waitcnt lgkmcnt(2)
	v_mfma_f32_32x32x16_bf16 v[96:111], v[88:91], v[160:163], v[96:111]
	v_mfma_f32_32x32x16_bf16 v[64:79], v[88:91], v[136:139], v[64:79]
	ds_read_b128 v[80:83], v92 offset:128
	ds_read_b128 v[88:91], v92 offset:160
	ds_read_b128 v[242:245], v92 offset:6784
	ds_read_b128 v[246:249], v92 offset:6816
	v_mfma_f32_32x32x16_bf16 v[112:127], v[84:87], v[172:175], 0
	s_waitcnt lgkmcnt(3)
	v_mfma_f32_32x32x16_bf16 v[96:111], v[80:83], v[156:159], v[96:111]
	v_mfma_f32_32x32x16_bf16 v[64:79], v[80:83], v[132:135], v[64:79]
	v_mfma_f32_32x32x16_bf16 v[112:127], v[216:219], v[168:171], v[112:127]
	s_waitcnt lgkmcnt(2)
	v_mfma_f32_32x32x16_bf16 v[96:111], v[88:91], v[152:155], v[96:111]
	v_mfma_f32_32x32x16_bf16 v[64:79], v[88:91], v[128:131], v[64:79]
	v_mfma_f32_32x32x16_bf16 v[80:95], v[84:87], v[148:151], 0
	v_mfma_f32_32x32x16_bf16 v[112:127], v[220:223], v[164:167], v[112:127]
	v_mfma_f32_32x32x16_bf16 v[80:95], v[216:219], v[140:143], v[80:95]
	v_mfma_f32_32x32x16_bf16 v[112:127], v[224:227], v[160:163], v[112:127]
	v_mfma_f32_32x32x16_bf16 v[80:95], v[220:223], v[144:147], v[80:95]
	s_waitcnt lgkmcnt(1)
	v_mfma_f32_32x32x16_bf16 v[112:127], v[242:245], v[156:159], v[112:127]
	v_mfma_f32_32x32x16_bf16 v[80:95], v[224:227], v[136:139], v[80:95]
	s_waitcnt lgkmcnt(0)
	v_mfma_f32_32x32x16_bf16 v[112:127], v[246:249], v[152:155], v[112:127]
	v_mfma_f32_32x32x16_bf16 v[80:95], v[242:245], v[132:135], v[80:95]
	v_mfma_f32_32x32x16_bf16 v[80:95], v[246:249], v[128:131], v[80:95]
.Lat_mm_skip:
	s_mul_i32 s38, s37, 0x3400
	s_waitcnt vmcnt(0)
	v_add3_u32 v216, s38, v205, v206
	ds_write_b128 v216, v[184:187]
	s_and_saveexec_b64 s[20:21], s[8:9]
	v_add3_u32 v216, s38, v208, v207
	ds_write_b128 v216, v[176:179]
	s_or_b64 exec, exec, s[20:21]
	s_xor_b32 s38, s37, 1
	s_mulk_i32 s38, 0x2200
	v_add_u32_e32 v216, s38, v209
	v_add_u32_e32 v216, 0x6800, v216
	ds_write2_b64 v216, v[180:181], v[182:183] offset1:1
	global_load_dwordx4 v[184:187], v[196:197], off
	s_and_saveexec_b64 s[10:11], s[8:9]
	s_cbranch_execz .Lat_k1
	global_load_dwordx4 v[176:179], v[192:193], off
.Lat_k1:
	s_or_b64 exec, exec, s[10:11]
	global_load_dwordx4 v[180:183], v[194:195], off
	v_lshl_add_u64 v[192:193], v[192:193], 0, s[86:87]
	v_lshl_add_u64 v[194:195], v[194:195], 0, s[72:73]
	v_lshl_add_u64 v[196:197], v[196:197], 0, s[86:87]
	s_add_i32 s36, s36, 1
	s_waitcnt lgkmcnt(0)
	s_barrier
	s_cmp_le_u32 s36, s35
	s_cbranch_scc1 .Lat_loop
	s_cmpk_lt_u32 s1, 0x100
	s_cbranch_scc0 .LBB0_1077
	s_barrier
